# speedup vs baseline: 1.0271x; 1.0023x over previous
; __device__ __forceinline__ void phase_prep() {
;     ...
;   if (blockIdx.x == 0 && tid < 2) {
;     const int l = tid; float s1 = 0, s2 = 0;
;     for (int i = 0; i < 64; ++i) { s1 += p.da_lq1[l * 64 + i] * p.da_lk1[l * 64 + i]; s2 += p.da_lq2[l * 64 + i] * p.da_lk2[l * 64 + i]; }
;     ((float*)(p.ws + OFF_LAM))[l] = expf(s1) - expf(s2) + lam_init_of(l);
;     float mq = 0, mk = 0;
;     for (int i = 0; i < 64; ++i) { mq = fmaxf(mq, fabsf(p.da_q_g[l * 64 + i])); mk = fmaxf(mk, fabsf(p.da_k_g[l * 64 + i])); }
;     ((float*)(p.ws + OFF_LAM))[2 + l] = -(8.f * mq * mk * LOG2E * 1.02f + 0.05f);
;   }
.LBB0_40:
	s_cmp_eq_u32 s77, 0xff
	s_cselect_b64 s[2:3], -1, 0
	v_cmp_gt_i32_e32 vcc, 2, v2
	s_and_b64 s[2:3], s[2:3], vcc
	s_and_saveexec_b64 s[4:5], s[2:3]
	s_cbranch_execz .LBB0_46
	s_load_dwordx8 s[12:19], s[6:7], 0x80
	v_lshlrev_b32_e32 v4, 6, v2
	v_ashrrev_i32_e32 v5, 31, v4
	v_lshlrev_b64 v[4:5], 2, v[4:5]
	v_mov_b32_e32 v6, 0
	s_waitcnt lgkmcnt(0)
	v_lshl_add_u64 v[8:9], s[18:19], 0, v[4:5]
	v_lshl_add_u64 v[10:11], s[16:17], 0, v[4:5]
	v_lshl_add_u64 v[12:13], s[12:13], 0, v[4:5]
	v_lshl_add_u64 v[14:15], s[14:15], 0, v[4:5]
	s_mov_b64 s[10:11], 0
	v_mov_b32_e32 v7, v6
